# v52 plus up-epilogue row-stat loads hoisted above the K-loop and memory-attention extra-Q fragments prefetched per tile
# speedup vs baseline: 1.0154x; 1.0003x over previous
.LBB0_461:
	s_cmp_eq_u32 s49, 4
	v_readlane_b32 s14, v254, 18
	s_cselect_b64 s[12:13], -1, 0
	v_readlane_b32 s15, v254, 19
	s_and_b64 s[12:13], s[14:15], s[12:13]
	v_readlane_b32 s14, v254, 22
	v_readlane_b32 s15, v254, 23
	s_and_b64 s[14:15], s[12:13], s[14:15]
	s_and_b64 s[12:13], s[12:13], exec
	s_cselect_b32 s0, 0x380, s0
	s_add_i32 s51, s0, s2
	s_cmpk_gt_i32 s51, 0x47f
	s_cselect_b64 s[0:1], -1, 0
	s_or_b64 s[0:1], s[14:15], s[0:1]
	s_and_b64 vcc, exec, s[0:1]
	s_cbranch_vccnz .LBB0_460
	v_readlane_b32 s54, v253, 0
	v_readlane_b32 s55, v253, 1
	s_mov_b32 s50, s95
	s_cmpk_gt_i32 s51, 0xff
	s_mov_b64 s[0:1], -1
	v_mbcnt_lo_u32_b32 v176, -1, 0
	v_mbcnt_hi_u32_b32 v176, -1, v176
	s_cbranch_scc0 .LBB0_802
	s_cmpk_gt_u32 s51, 0x1ff
	s_cbranch_scc0 .LBB0_699
	s_cmpk_gt_u32 s51, 0x37f
	s_cbranch_scc0 .LBB0_480
	s_lshl_b32 s19, s51, 7
	s_mov_b32 s0, s83
	s_lshl_b32 s1, s0, 1
	s_bfe_u32 s12, s19, 0x1000c
	s_or_b32 s1, s1, s12
	s_and_b32 s18, s19, 0x1f00
	s_add_i32 s1, s1, -2
	s_cmp_lt_i32 s0, 2
	s_cselect_b32 s0, s0, s1
	s_ashr_i32 s1, s0, 31
	s_lshl_b64 s[0:1], s[0:1], 20
	s_add_u32 s0, s54, s0
	s_addc_u32 s1, s55, s1
	s_lshl_b32 s12, s51, 2
	s_and_b32 s12, s12, 0xffffff00
	s_add_i32 s26, s12, 0xfffff200
	s_lshl_b64 s[14:15], s[26:27], 1
	s_add_u32 s0, s0, s14
	s_addc_u32 s1, s1, s15
	s_add_u32 s12, s0, 0xa043000
	s_addc_u32 s13, s1, 0
	s_lshl_b32 s0, s87, 1
	s_add_u32 s0, s54, s0
	s_addc_u32 s1, s55, 0
	s_mul_i32 s22, s18, 0x6600
	s_add_u32 s0, s0, s22
	s_addc_u32 s1, s1, 0
	s_add_u32 s0, s0, s14
	s_addc_u32 s1, s1, s15
	s_add_u32 s0, s0, 0x12a45e00
	s_addc_u32 s1, s1, 0
	s_and_b32 s19, s19, 0x80
	s_lshl_b32 s19, s19, 1
	s_add_u32 s22, s12, s19
	v_mbcnt_lo_u32_b32 v2, -1, 0
	v_mbcnt_hi_u32_b32 v2, -1, v2
	s_addc_u32 s23, s13, 0
	v_add_u32_e32 v26, s65, v2
	v_and_b32_e32 v0, 0x3fffffc0, v26
	s_add_i32 s24, 0, 0x18000
	v_lshl_add_u32 v179, v0, 2, s24
	v_ashrrev_i32_e32 v154, 1, v26
	s_movk_i32 s24, 0xffe0
	v_bfe_u32 v177, v2, 5, 1
	v_bfi_b32 v3, s24, v154, v2
	v_mov_b64_e32 v[0:1], s[0:1]
	v_ashrrev_i32_e32 v170, 4, v26
	v_mad_i64_i32 v[0:1], s[0:1], v3, s40, v[0:1]
	v_lshlrev_b32_e32 v96, 4, v177
	v_and_b32_e32 v3, 0xfffff0, v170
	v_lshlrev_b32_e32 v4, 1, v170
	v_lshl_add_u64 v[168:169], v[0:1], 0, v[96:97]
	v_lshlrev_b32_e32 v0, 3, v2
	v_and_or_b32 v3, v4, 8, v3
	v_and_b32_e32 v1, 0x78, v0
	v_lshrrev_b32_e32 v4, 1, v170
	v_lshrrev_b32_e32 v3, 1, v3
	v_bfe_u32 v0, v0, 5, 2
	v_and_b32_e32 v5, 3, v170
	v_or_b32_e32 v3, v3, v0
	v_and_or_b32 v4, v4, 4, v5
	v_lshlrev_b32_e32 v34, 1, v1
	v_lshlrev_b32_e32 v3, 9, v3
	v_lshlrev_b32_e32 v4, 6, v4
	v_and_b32_e32 v1, 48, v34
	v_add_u32_e32 v24, 32, v170
	v_or3_b32 v27, v3, v4, v1
	v_and_b32_e32 v3, 0xfffff0, v24
	v_lshlrev_b32_e32 v5, 1, v24
	v_and_or_b32 v3, v5, 8, v3
	v_lshrrev_b32_e32 v3, 1, v3
	v_or_b32_e32 v0, v3, v0
	v_and_b32_e32 v36, 63, v2
	v_lshlrev_b32_e32 v0, 9, v0
	v_lshlrev_b32_e32 v29, 4, v2
	v_and_b32_e32 v178, 31, v2
	v_or3_b32 v28, v0, v4, v1
	v_lshlrev_b32_e32 v0, 3, v36
	v_and_b32_e32 v1, 0xc0, v29
	v_lshlrev_b32_e32 v2, 1, v2
	v_ashrrev_i32_e32 v171, 31, v170
	v_and_or_b32 v1, v0, 24, v1
	v_and_b32_e32 v2, 32, v2
	v_and_b32_e32 v0, 0x100, v0
	v_lshlrev_b64 v[32:33], 12, v[170:171]
	v_or3_b32 v155, v1, v2, v0
	v_lshl_add_u64 v[0:1], s[22:23], 0, v[32:33]
	v_mov_b32_e32 v35, v97
	v_lshl_add_u64 v[0:1], v[0:1], 0, v[34:35]
	global_load_dwordx4 v[126:129], v[168:169], off
	global_load_dwordx4 v[122:125], v[168:169], off offset:32
	global_load_dwordx4 v[118:121], v[168:169], off offset:64
	global_load_dwordx4 v[114:117], v[168:169], off offset:96
	global_load_dwordx4 v[110:113], v[168:169], off offset:128
	global_load_dwordx4 v[106:109], v[168:169], off offset:160
	global_load_dwordx4 v[102:105], v[168:169], off offset:192
	global_load_dwordx4 v[98:101], v[168:169], off offset:224
	v_ashrrev_i32_e32 v25, 31, v24
	global_load_dwordx4 v[0:3], v[0:1], off offset:2048
	v_lshlrev_b64 v[12:13], 12, v[24:25]
	v_lshl_add_u64 v[4:5], s[22:23], 0, v[12:13]
	v_lshl_add_u64 v[8:9], s[12:13], 0, v[32:33]
	v_lshl_add_u64 v[12:13], s[12:13], 0, v[12:13]
	v_lshl_add_u64 v[4:5], v[4:5], 0, v[34:35]
	v_lshl_add_u64 v[16:17], v[8:9], 0, v[34:35]
	v_lshl_add_u64 v[20:21], v[12:13], 0, v[34:35]
	global_load_dwordx4 v[4:7], v[4:5], off offset:2048
	v_add_u32_e32 v190, 0, v27
	global_load_dwordx4 v[8:11], v[16:17], off
	global_load_dwordx4 v[12:15], v[20:21], off
	s_nop 0
	global_load_dwordx4 v[16:19], v[16:17], off offset:256
	s_nop 0
	global_load_dwordx4 v[20:23], v[20:21], off offset:256
	s_waitcnt vmcnt(0)
	v_lshlrev_b32_e32 v47, 8, v178
	s_movk_i32 s1, 0x70
	s_add_i32 s0, 0, 0x10000
	v_add_u32_e32 v56, 0, v47
	v_bitop3_b32 v46, v96, v29, s1 bitop3:0x78
	v_add_u32_e32 v191, 0, v28
	v_add_u32_e32 v182, v56, v46
	v_and_b32_e32 v37, 0x70, v29
	v_bitop3_b32 v44, v96, v37, 32 bitop3:0x36
	v_add_u32_e32 v183, v56, v44
	v_bitop3_b32 v42, v96, v37, 64 bitop3:0x36
	v_add_u32_e32 v184, v56, v42
	s_movk_i32 s1, 0x60
	v_add_u32_e32 v60, s0, v47
	v_add_u32_e32 v156, v60, v46
	v_add_u32_e32 v157, v60, v44
	v_add_u32_e32 v205, v60, v42
	s_mov_b32 s26, 0x43000000
	s_cmp_lg_u32 0, -1
	s_mov_b64 s[24:25], 0x40000
	v_lshl_add_u64 v[174:175], s[22:23], 0, v[34:35]
	v_lshl_add_u64 v[172:173], s[12:13], 0, v[34:35]
	v_cmp_gt_u32_e64 s[34:35], 32, v36
	v_lshl_add_u32 v181, v178, 2, v179
	s_waitcnt vmcnt(5)
	ds_write_b128 v190, v[0:3]
	v_lshlrev_b32_e32 v0, 8, v170
	v_and_b32_e32 v1, 0x70, v26
	v_bitop3_b32 v43, v34, v0, v1 bitop3:0xde
	v_lshlrev_b32_e32 v0, 8, v24
	v_bitop3_b32 v45, v0, v34, v1 bitop3:0xf6
	v_add_u32_e32 v192, 0, v43
	v_add_u32_e32 v193, 0, v45
	v_add_u32_e32 v203, s0, v43
	v_add_u32_e32 v204, s0, v45
	s_waitcnt vmcnt(4)
	ds_write_b128 v191, v[4:7]
	s_waitcnt vmcnt(3)
	ds_write_b128 v192, v[8:11] offset:32768
	s_waitcnt vmcnt(2)
	ds_write_b128 v193, v[12:15] offset:32768
	s_waitcnt vmcnt(1)
	ds_write_b128 v203, v[16:19]
	s_waitcnt vmcnt(0)
	ds_write_b128 v204, v[20:23]
	s_waitcnt lgkmcnt(0)
	s_barrier
	global_load_dwordx4 v[216:219], v[168:169], off offset:256
	global_load_dwordx4 v[220:223], v[168:169], off offset:288
	global_load_dwordx4 v[224:227], v[168:169], off offset:320
	global_load_dwordx4 v[228:231], v[168:169], off offset:352
	global_load_dwordx4 v[232:235], v[168:169], off offset:384
	global_load_dwordx4 v[236:239], v[168:169], off offset:416
	global_load_dwordx4 v[240:243], v[168:169], off offset:448
	global_load_dwordx4 v[244:247], v[168:169], off offset:480
	ds_read_b128 v[0:3], v182 offset:32768
	ds_read_b128 v[4:7], v182 offset:40960
	s_waitcnt lgkmcnt(1)
	v_mfma_f32_32x32x16_bf16 v[16:31], v[0:3], v[126:129], 0
	ds_read_b128 v[38:41], v183 offset:32768
	ds_read_b128 v[48:51], v183 offset:40960
	s_cselect_b32 s0, 0, 0
	v_add_u32_e32 v180, s0, v155
	s_waitcnt lgkmcnt(2)
	v_mfma_f32_32x32x16_bf16 v[0:15], v[4:7], v[126:129], 0
	s_waitcnt lgkmcnt(1)
	v_mfma_f32_32x32x16_bf16 v[16:31], v[38:41], v[122:125], v[16:31]
	s_waitcnt lgkmcnt(0)
	v_mfma_f32_32x32x16_bf16 v[0:15], v[48:51], v[122:125], v[0:15]
	ds_read_b128 v[38:41], v184 offset:32768
	ds_read_b128 v[48:51], v184 offset:40960
	s_waitcnt lgkmcnt(1)
	v_mfma_f32_32x32x16_bf16 v[16:31], v[38:41], v[118:121], v[16:31]
	v_bitop3_b32 v41, v96, v37, s1 bitop3:0x36
	v_add_u32_e32 v185, v56, v41
	s_movk_i32 s1, 0x80
	v_bitop3_b32 v40, v96, v37, s1 bitop3:0x36
	v_add_u32_e32 v186, v56, v40
	s_movk_i32 s1, 0xa0
	v_bitop3_b32 v39, v96, v37, s1 bitop3:0x36
	s_waitcnt lgkmcnt(0)
	v_mfma_f32_32x32x16_bf16 v[0:15], v[48:51], v[118:121], v[0:15]
	ds_read_b128 v[48:51], v185 offset:32768
	ds_read_b128 v[52:55], v185 offset:40960
	v_add_u32_e32 v187, v56, v39
	s_movk_i32 s1, 0xc0
	v_bitop3_b32 v38, v96, v37, s1 bitop3:0x36
	v_add_u32_e32 v188, v56, v38
	s_movk_i32 s1, 0xe0
	v_bitop3_b32 v37, v96, v37, s1 bitop3:0x36
	s_waitcnt lgkmcnt(1)
	v_mfma_f32_32x32x16_bf16 v[16:31], v[48:51], v[114:117], v[16:31]
	v_add_u32_e32 v189, v56, v37
	v_add_u32_e32 v207, v60, v41
	v_add_u32_e32 v209, v60, v40
	v_add_u32_e32 v210, v60, v39
	v_add_u32_e32 v211, v60, v38
	v_add_u32_e32 v206, v60, v37
	s_waitcnt lgkmcnt(0)
	v_mfma_f32_32x32x16_bf16 v[0:15], v[52:55], v[114:117], v[0:15]
	ds_read_b128 v[48:51], v186 offset:32768
	ds_read_b128 v[52:55], v186 offset:40960
	s_waitcnt lgkmcnt(1)
	v_mfma_f32_32x32x16_bf16 v[16:31], v[48:51], v[110:113], v[16:31]
	s_waitcnt lgkmcnt(0)
	v_mfma_f32_32x32x16_bf16 v[0:15], v[52:55], v[110:113], v[0:15]
	ds_read_b128 v[48:51], v187 offset:32768
	ds_read_b128 v[52:55], v187 offset:40960
	s_waitcnt lgkmcnt(1)
	v_mfma_f32_32x32x16_bf16 v[16:31], v[48:51], v[106:109], v[16:31]
	s_waitcnt lgkmcnt(0)
	v_mfma_f32_32x32x16_bf16 v[0:15], v[52:55], v[106:109], v[0:15]
	ds_read_b128 v[48:51], v188 offset:32768
	ds_read_b128 v[52:55], v188 offset:40960
	s_waitcnt lgkmcnt(1)
	v_mfma_f32_32x32x16_bf16 v[16:31], v[48:51], v[102:105], v[16:31]
	s_waitcnt lgkmcnt(0)
	v_mfma_f32_32x32x16_bf16 v[0:15], v[52:55], v[102:105], v[0:15]
	ds_read_b128 v[48:51], v189 offset:32768
	ds_read_b128 v[52:55], v189 offset:40960
	s_waitcnt lgkmcnt(1)
	v_mfma_f32_32x32x16_bf16 v[16:31], v[48:51], v[98:101], v[16:31]
	s_waitcnt lgkmcnt(0)
	v_mfma_f32_32x32x16_bf16 v[0:15], v[52:55], v[98:101], v[0:15]
	ds_read_b128 v[48:51], v156
	ds_read_b128 v[52:55], v156 offset:8192
	s_waitcnt vmcnt(7) lgkmcnt(1)
	v_mfma_f32_32x32x16_bf16 v[16:31], v[48:51], v[216:219], v[16:31]
	s_waitcnt lgkmcnt(0)
	v_mfma_f32_32x32x16_bf16 v[0:15], v[52:55], v[216:219], v[0:15]
	ds_read_b128 v[48:51], v157
	ds_read_b128 v[52:55], v157 offset:8192
	s_waitcnt vmcnt(6) lgkmcnt(1)
	v_mfma_f32_32x32x16_bf16 v[16:31], v[48:51], v[220:223], v[16:31]
	s_waitcnt lgkmcnt(0)
	v_mfma_f32_32x32x16_bf16 v[0:15], v[52:55], v[220:223], v[0:15]
	ds_read_b128 v[48:51], v205
	ds_read_b128 v[52:55], v205 offset:8192
	s_waitcnt vmcnt(5) lgkmcnt(1)
	v_mfma_f32_32x32x16_bf16 v[16:31], v[48:51], v[224:227], v[16:31]
	s_waitcnt lgkmcnt(0)
	v_mfma_f32_32x32x16_bf16 v[0:15], v[52:55], v[224:227], v[0:15]
	ds_read_b128 v[48:51], v207
	ds_read_b128 v[52:55], v207 offset:8192
	s_waitcnt vmcnt(4) lgkmcnt(1)
	v_mfma_f32_32x32x16_bf16 v[16:31], v[48:51], v[228:231], v[16:31]
	s_waitcnt lgkmcnt(0)
	v_mfma_f32_32x32x16_bf16 v[0:15], v[52:55], v[228:231], v[0:15]
	ds_read_b128 v[48:51], v209
	ds_read_b128 v[52:55], v209 offset:8192
	s_waitcnt vmcnt(3) lgkmcnt(1)
	v_mfma_f32_32x32x16_bf16 v[16:31], v[48:51], v[232:235], v[16:31]
	s_waitcnt lgkmcnt(0)
	v_mfma_f32_32x32x16_bf16 v[0:15], v[52:55], v[232:235], v[0:15]
	ds_read_b128 v[48:51], v210
	ds_read_b128 v[52:55], v210 offset:8192
	s_waitcnt vmcnt(2) lgkmcnt(1)
	v_mfma_f32_32x32x16_bf16 v[16:31], v[48:51], v[236:239], v[16:31]
	s_waitcnt lgkmcnt(0)
	v_mfma_f32_32x32x16_bf16 v[0:15], v[52:55], v[236:239], v[0:15]
	ds_read_b128 v[48:51], v211
	ds_read_b128 v[52:55], v211 offset:8192
	s_waitcnt vmcnt(1) lgkmcnt(1)
	v_mfma_f32_32x32x16_bf16 v[16:31], v[48:51], v[240:243], v[16:31]
	s_waitcnt lgkmcnt(0)
	v_mfma_f32_32x32x16_bf16 v[0:15], v[52:55], v[240:243], v[0:15]
	ds_read_b128 v[48:51], v206
	ds_read_b128 v[52:55], v206 offset:8192
	s_waitcnt vmcnt(0) lgkmcnt(1)
	v_mfma_f32_32x32x16_bf16 v[16:31], v[48:51], v[244:247], v[16:31]
	s_nop 11
	v_max_f32_e32 v48, v17, v17
	v_max_f32_e32 v49, v16, v16
	s_waitcnt lgkmcnt(0)
	v_mfma_f32_32x32x16_bf16 v[0:15], v[52:55], v[244:247], v[0:15]
	v_max_f32_e32 v48, v49, v48
	v_max3_f32 v48, v48, v18, v19
	v_max3_f32 v48, v48, v20, v21
	v_max3_f32 v48, v48, v22, v23
	v_max3_f32 v48, v48, v24, v25
	v_max3_f32 v48, v48, v26, v27
	v_max3_f32 v48, v48, v28, v29
	v_max3_f32 v48, v48, v30, v31
	s_nop 3
	v_max3_f32 v48, v48, v0, v1
	v_max3_f32 v48, v48, v2, v3
	v_max3_f32 v48, v48, v4, v5
	v_max3_f32 v48, v48, v6, v7
	v_max3_f32 v48, v48, v8, v9
	v_max3_f32 v48, v48, v10, v11
	v_max3_f32 v48, v48, v12, v13
	v_max3_f32 v48, v48, v14, v15
	v_mov_b32_e32 v49, v48
	s_nop 1
	v_permlane32_swap_b32_e32 v48, v49
	v_max_f32_e32 v49, v49, v49
	v_max_f32_e32 v48, v48, v48
	v_max_f32_e32 v48, v48, v49
	v_add_f32_e32 v49, 0x7149f2ca, v48
	v_cmp_ge_f32_e32 vcc, s26, v49
	s_cmp_eq_u64 vcc, exec
	s_cselect_b64 s[0:1], -1, 0
	v_max_f32_e32 v220, 0xf149f2ca, v48
	v_cndmask_b32_e64 v208, v220, v251, s[0:1]
	v_mul_f32_e32 v56, 0xbdb8aa3b, v208
	v_fmamk_f32 v63, v8, 0x3db8aa3b, v56
	v_fmamk_f32 v130, v9, 0x3db8aa3b, v56
	v_lshl_add_u64 v[8:9], v[32:33], 0, s[24:25]
	s_mov_b64 s[24:25], 0x60000
	v_fmamk_f32 v133, v0, 0x3db8aa3b, v56
	v_fmamk_f32 v134, v1, 0x3db8aa3b, v56
	v_fmamk_f32 v57, v12, 0x3db8aa3b, v56
	v_fmamk_f32 v58, v13, 0x3db8aa3b, v56
	v_lshl_add_u64 v[12:13], v[32:33], 0, s[24:25]
	v_lshl_add_u64 v[0:1], s[22:23], 0, v[8:9]
	v_fmamk_f32 v16, v16, 0x3db8aa3b, v56
	v_fmamk_f32 v17, v17, 0x3db8aa3b, v56
	v_fmamk_f32 v20, v20, 0x3db8aa3b, v56
	v_fmamk_f32 v21, v21, 0x3db8aa3b, v56
	v_fmamk_f32 v137, v4, 0x3db8aa3b, v56
	v_fmamk_f32 v60, v5, 0x3db8aa3b, v56
	v_lshl_add_u64 v[0:1], v[0:1], 0, v[34:35]
	v_lshl_add_u64 v[4:5], s[22:23], 0, v[12:13]
	v_lshl_add_u64 v[8:9], s[12:13], 0, v[8:9]
	v_lshl_add_u64 v[12:13], s[12:13], 0, v[12:13]
	v_fmamk_f32 v18, v18, 0x3db8aa3b, v56
	v_fmamk_f32 v19, v19, 0x3db8aa3b, v56
	v_fmamk_f32 v22, v22, 0x3db8aa3b, v56
	v_fmamk_f32 v23, v23, 0x3db8aa3b, v56
	v_fmamk_f32 v135, v2, 0x3db8aa3b, v56
	v_fmamk_f32 v136, v3, 0x3db8aa3b, v56
	v_exp_f32_e32 v48, v16
	v_exp_f32_e32 v49, v17
	v_exp_f32_e32 v54, v20
	v_exp_f32_e32 v55, v21
	global_load_dwordx4 v[0:3], v[0:1], off offset:2048
	v_lshl_add_u64 v[4:5], v[4:5], 0, v[34:35]
	v_lshl_add_u64 v[16:17], v[8:9], 0, v[34:35]
	v_lshl_add_u64 v[20:21], v[12:13], 0, v[34:35]
	v_fmamk_f32 v24, v24, 0x3db8aa3b, v56
	v_fmamk_f32 v25, v25, 0x3db8aa3b, v56
	v_fmamk_f32 v26, v26, 0x3db8aa3b, v56
	v_fmamk_f32 v64, v27, 0x3db8aa3b, v56
	v_fmamk_f32 v28, v28, 0x3db8aa3b, v56
	v_fmamk_f32 v65, v29, 0x3db8aa3b, v56
	v_fmamk_f32 v66, v30, 0x3db8aa3b, v56
	v_fmamk_f32 v67, v31, 0x3db8aa3b, v56
	v_fmamk_f32 v61, v6, 0x3db8aa3b, v56
	v_fmamk_f32 v62, v7, 0x3db8aa3b, v56
	v_fmamk_f32 v131, v10, 0x3db8aa3b, v56
	v_fmamk_f32 v132, v11, 0x3db8aa3b, v56
	v_fmamk_f32 v59, v14, 0x3db8aa3b, v56
	v_fmac_f32_e32 v56, 0x3db8aa3b, v15
	v_exp_f32_e32 v50, v18
	v_exp_f32_e32 v53, v19
	v_exp_f32_e32 v51, v22
	v_exp_f32_e32 v52, v23
	global_load_dwordx4 v[4:7], v[4:5], off offset:2048
	v_exp_f32_e32 v27, v24
	global_load_dwordx4 v[8:11], v[16:17], off
	global_load_dwordx4 v[12:15], v[20:21], off
	s_nop 0
	global_load_dwordx4 v[16:19], v[16:17], off offset:256
	s_nop 0
	global_load_dwordx4 v[20:23], v[20:21], off offset:256
	v_exp_f32_e32 v29, v25
	v_exp_f32_e32 v30, v26
	v_exp_f32_e32 v31, v64
	v_exp_f32_e32 v24, v28
	v_exp_f32_e32 v25, v65
	v_exp_f32_e32 v26, v66
	v_exp_f32_e32 v28, v67
	s_waitcnt vmcnt(0)
	s_add_i32 s24, 0, 0x14000
	s_waitcnt vmcnt(5)
	ds_write_b128 v190, v[0:3] offset:16384
	s_waitcnt vmcnt(4)
	ds_write_b128 v191, v[4:7] offset:16384
	s_waitcnt vmcnt(3)
	ds_write_b128 v192, v[8:11] offset:49152
	s_waitcnt vmcnt(2)
	ds_write_b128 v193, v[12:15] offset:49152
	v_add_u32_e32 v221, s24, v43
	v_add_u32_e32 v222, s24, v45
	v_add_u32_e32 v12, s24, v47
	s_waitcnt vmcnt(1)
	ds_write_b128 v221, v[16:19]
	s_waitcnt vmcnt(0)
	ds_write_b128 v222, v[20:23]
	s_waitcnt lgkmcnt(0)
	s_barrier
	global_load_dwordx4 v[224:227], v[168:169], off offset:256
	global_load_dwordx4 v[228:231], v[168:169], off offset:288
	global_load_dwordx4 v[232:235], v[168:169], off offset:320
	global_load_dwordx4 v[236:239], v[168:169], off offset:352
	global_load_dwordx4 v[240:243], v[168:169], off offset:384
	global_load_dwordx4 v[244:247], v[168:169], off offset:416
	global_load_dwordx4 v[138:141], v[168:169], off offset:448
	global_load_dwordx4 v[142:145], v[168:169], off offset:480
	ds_read_b128 v[0:3], v182 offset:49152
	ds_read_b128 v[4:7], v182 offset:57344
	v_add_u32_e32 v212, v12, v46
	v_add_u32_e32 v213, v12, v44
	v_add_u32_e32 v215, v12, v42
	s_waitcnt lgkmcnt(1)
	v_mfma_f32_32x32x16_bf16 v[80:95], v[0:3], v[126:129], 0
	v_add_u32_e32 v214, v12, v41
	v_add_u32_e32 v217, v12, v40
	v_add_u32_e32 v216, v12, v39
	v_add_u32_e32 v218, v12, v38
	v_add_u32_e32 v219, v12, v37
	v_add_f32_e32 v16, 0, v48
	v_add_f32_e32 v16, v49, v16
	s_waitcnt lgkmcnt(0)
	v_mfma_f32_32x32x16_bf16 v[64:79], v[4:7], v[126:129], 0
	ds_read_b128 v[0:3], v183 offset:49152
	ds_read_b128 v[4:7], v183 offset:57344
	v_add_f32_e32 v16, v50, v16
	v_add_f32_e32 v16, v53, v16
	v_add_f32_e32 v16, v54, v16
	v_add_f32_e32 v16, v55, v16
	v_add_f32_e32 v16, v51, v16
	v_add_f32_e32 v16, v52, v16
	s_waitcnt lgkmcnt(1)
	v_mfma_f32_32x32x16_bf16 v[80:95], v[0:3], v[122:125], v[80:95]
	v_add_f32_e32 v16, v27, v16
	v_add_f32_e32 v16, v29, v16
	v_add_f32_e32 v16, v30, v16
	v_add_f32_e32 v16, v31, v16
	v_add_f32_e32 v16, v24, v16
	v_add_f32_e32 v16, v25, v16
	v_add_f32_e32 v16, v26, v16
	s_waitcnt lgkmcnt(0)
	v_mfma_f32_32x32x16_bf16 v[64:79], v[4:7], v[122:125], v[64:79]
	ds_read_b128 v[0:3], v184 offset:49152
	ds_read_b128 v[4:7], v184 offset:57344
	v_add_f32_e32 v16, v28, v16
	v_exp_f32_e32 v12, v57
	v_exp_f32_e32 v13, v58
	v_exp_f32_e32 v14, v59
	v_exp_f32_e32 v15, v56
	s_waitcnt lgkmcnt(1)
	v_mfma_f32_32x32x16_bf16 v[80:95], v[0:3], v[118:121], v[80:95]
	s_waitcnt lgkmcnt(0)
	v_mfma_f32_32x32x16_bf16 v[64:79], v[4:7], v[118:121], v[64:79]
	ds_read_b128 v[0:3], v185 offset:49152
	ds_read_b128 v[4:7], v185 offset:57344
	s_waitcnt lgkmcnt(1)
	v_mfma_f32_32x32x16_bf16 v[80:95], v[0:3], v[114:117], v[80:95]
	s_waitcnt lgkmcnt(0)
	v_mfma_f32_32x32x16_bf16 v[64:79], v[4:7], v[114:117], v[64:79]
	ds_read_b128 v[0:3], v186 offset:49152
	ds_read_b128 v[4:7], v186 offset:57344
	s_waitcnt lgkmcnt(1)
	v_mfma_f32_32x32x16_bf16 v[80:95], v[0:3], v[110:113], v[80:95]
	s_waitcnt lgkmcnt(0)
	v_mfma_f32_32x32x16_bf16 v[64:79], v[4:7], v[110:113], v[64:79]
	ds_read_b128 v[0:3], v187 offset:49152
	ds_read_b128 v[4:7], v187 offset:57344
	s_waitcnt lgkmcnt(1)
	v_mfma_f32_32x32x16_bf16 v[80:95], v[0:3], v[106:109], v[80:95]
	s_waitcnt lgkmcnt(0)
	v_mfma_f32_32x32x16_bf16 v[64:79], v[4:7], v[106:109], v[64:79]
	ds_read_b128 v[0:3], v188 offset:49152
	ds_read_b128 v[4:7], v188 offset:57344
	s_waitcnt lgkmcnt(1)
	v_mfma_f32_32x32x16_bf16 v[80:95], v[0:3], v[102:105], v[80:95]
	s_waitcnt lgkmcnt(0)
	v_mfma_f32_32x32x16_bf16 v[64:79], v[4:7], v[102:105], v[64:79]
	ds_read_b128 v[0:3], v189 offset:49152
	ds_read_b128 v[4:7], v189 offset:57344
	s_waitcnt lgkmcnt(1)
	v_mfma_f32_32x32x16_bf16 v[80:95], v[0:3], v[98:101], v[80:95]
	s_waitcnt lgkmcnt(0)
	v_mfma_f32_32x32x16_bf16 v[64:79], v[4:7], v[98:101], v[64:79]
	ds_read_b128 v[0:3], v212
	ds_read_b128 v[4:7], v212 offset:8192
	s_waitcnt vmcnt(7) lgkmcnt(1)
	v_mfma_f32_32x32x16_bf16 v[80:95], v[0:3], v[224:227], v[80:95]
	s_waitcnt lgkmcnt(0)
	v_mfma_f32_32x32x16_bf16 v[64:79], v[4:7], v[224:227], v[64:79]
	ds_read_b128 v[0:3], v213
	ds_read_b128 v[4:7], v213 offset:8192
	s_waitcnt vmcnt(6) lgkmcnt(1)
	v_mfma_f32_32x32x16_bf16 v[80:95], v[0:3], v[228:231], v[80:95]
	s_waitcnt lgkmcnt(0)
	v_mfma_f32_32x32x16_bf16 v[64:79], v[4:7], v[228:231], v[64:79]
	ds_read_b128 v[0:3], v215
	ds_read_b128 v[4:7], v215 offset:8192
	s_waitcnt vmcnt(5) lgkmcnt(1)
	v_mfma_f32_32x32x16_bf16 v[80:95], v[0:3], v[232:235], v[80:95]
	s_waitcnt lgkmcnt(0)
	v_mfma_f32_32x32x16_bf16 v[64:79], v[4:7], v[232:235], v[64:79]
	ds_read_b128 v[0:3], v214
	ds_read_b128 v[4:7], v214 offset:8192
	s_waitcnt vmcnt(4) lgkmcnt(1)
	v_mfma_f32_32x32x16_bf16 v[80:95], v[0:3], v[236:239], v[80:95]
	s_waitcnt lgkmcnt(0)
	v_mfma_f32_32x32x16_bf16 v[64:79], v[4:7], v[236:239], v[64:79]
	ds_read_b128 v[0:3], v217
	ds_read_b128 v[4:7], v217 offset:8192
	s_waitcnt vmcnt(3) lgkmcnt(1)
	v_mfma_f32_32x32x16_bf16 v[80:95], v[0:3], v[240:243], v[80:95]
	s_waitcnt lgkmcnt(0)
	v_mfma_f32_32x32x16_bf16 v[64:79], v[4:7], v[240:243], v[64:79]
	ds_read_b128 v[0:3], v216
	ds_read_b128 v[4:7], v216 offset:8192
	s_waitcnt vmcnt(2) lgkmcnt(1)
	v_mfma_f32_32x32x16_bf16 v[80:95], v[0:3], v[244:247], v[80:95]
	s_waitcnt lgkmcnt(0)
	v_mfma_f32_32x32x16_bf16 v[64:79], v[4:7], v[244:247], v[64:79]
	ds_read_b128 v[0:3], v218
	ds_read_b128 v[4:7], v218 offset:8192
	s_waitcnt vmcnt(1) lgkmcnt(1)
	v_mfma_f32_32x32x16_bf16 v[80:95], v[0:3], v[138:141], v[80:95]
	s_waitcnt lgkmcnt(0)
	v_mfma_f32_32x32x16_bf16 v[64:79], v[4:7], v[138:141], v[64:79]
	ds_read_b128 v[0:3], v219
	ds_read_b128 v[4:7], v219 offset:8192
	v_cvt_pk_bf16_f32 v48, v48, v49
	v_cvt_pk_bf16_f32 v49, v50, v53
	v_cvt_pk_bf16_f32 v50, v54, v55
	v_cvt_pk_bf16_f32 v51, v51, v52
	v_cvt_pk_bf16_f32 v196, v27, v29
	s_waitcnt vmcnt(0) lgkmcnt(1)
	v_mfma_f32_32x32x16_bf16 v[80:95], v[0:3], v[142:145], v[80:95]
	v_exp_f32_e32 v0, v133
	v_exp_f32_e32 v1, v134
	v_exp_f32_e32 v2, v135
	v_exp_f32_e32 v3, v136
	v_add_f32_e32 v16, v0, v16
	v_add_f32_e32 v16, v1, v16
	v_add_f32_e32 v16, v2, v16
	s_waitcnt lgkmcnt(0)
	v_mfma_f32_32x32x16_bf16 v[64:79], v[4:7], v[142:145], v[64:79]
	v_exp_f32_e32 v4, v137
	v_exp_f32_e32 v5, v60
	v_exp_f32_e32 v6, v61
	v_exp_f32_e32 v7, v62
	v_add_f32_e32 v16, v3, v16
	v_exp_f32_e32 v8, v63
	v_add_f32_e32 v16, v4, v16
	v_exp_f32_e32 v9, v130
	v_add_f32_e32 v16, v5, v16
	v_exp_f32_e32 v10, v131
	v_add_f32_e32 v16, v6, v16
	v_exp_f32_e32 v11, v132
	v_add_f32_e32 v16, v7, v16
	v_add_f32_e32 v16, v8, v16
	v_add_f32_e32 v16, v9, v16
	v_add_f32_e32 v16, v10, v16
	v_add_f32_e32 v16, v11, v16
	v_add_f32_e32 v16, v12, v16
	v_add_f32_e32 v16, v13, v16
	v_add_f32_e32 v16, v14, v16
	v_add_f32_e32 v200, v15, v16
	v_mov_b32_e32 v201, v200
	s_nop 1
	v_permlane32_swap_b32_e32 v200, v201
	v_permlane32_swap_b32_e32 v48, v50
	v_permlane32_swap_b32_e32 v49, v51
	v_cvt_pk_bf16_f32 v197, v30, v31
	v_cvt_pk_bf16_f32 v198, v24, v25
	v_cvt_pk_bf16_f32 v199, v26, v28
	v_cvt_pk_bf16_f32 v224, v0, v1
	v_cvt_pk_bf16_f32 v225, v2, v3
	v_cvt_pk_bf16_f32 v226, v4, v5
	v_cvt_pk_bf16_f32 v227, v6, v7
	v_cvt_pk_bf16_f32 v228, v8, v9
	v_cvt_pk_bf16_f32 v229, v10, v11
	v_cvt_pk_bf16_f32 v230, v12, v13
	v_cvt_pk_bf16_f32 v231, v14, v15
	s_nop 0
	v_permlane32_swap_b32_e32 v196, v198
	v_permlane32_swap_b32_e32 v197, v199
	v_permlane32_swap_b32_e32 v224, v226
	v_permlane32_swap_b32_e32 v225, v227
	v_permlane32_swap_b32_e32 v228, v230
	v_permlane32_swap_b32_e32 v229, v231
	s_mov_b64 s[12:13], 0x80000
	v_lshl_add_u64 v[0:1], v[32:33], 0, s[12:13]
	s_mov_b64 s[12:13], 0xa0000
	v_lshl_add_u64 v[2:3], v[32:33], 0, s[12:13]
	v_lshl_add_u64 v[4:5], v[174:175], 0, v[0:1]
	v_lshl_add_u64 v[0:1], v[172:173], 0, v[0:1]
	v_lshl_add_u64 v[6:7], v[174:175], 0, v[2:3]
	global_load_dwordx4 v[130:133], v[4:5], off offset:2048
	global_load_dwordx4 v[134:137], v[6:7], off offset:2048
	v_lshl_add_u64 v[2:3], v[172:173], 0, v[2:3]
	global_load_dwordx4 v[138:141], v[0:1], off
	global_load_dwordx4 v[142:145], v[0:1], off offset:256
	global_load_dwordx4 v[150:153], v[2:3], off
	global_load_dwordx4 v[146:149], v[2:3], off offset:256
	ds_read_b64_tr_b16 v[0:1], v180 offset:0
	ds_read_b64_tr_b16 v[2:3], v180 offset:0x800
	ds_read_b64_tr_b16 v[16:17], v180 offset:0x1000
	ds_read_b64_tr_b16 v[18:19], v180 offset:0x1800
	ds_read_b64_tr_b16 v[20:21], v180 offset:0x2000
	ds_read_b64_tr_b16 v[22:23], v180 offset:0x2800
	ds_read_b64_tr_b16 v[24:25], v180 offset:0x3000
	ds_read_b64_tr_b16 v[26:27], v180 offset:0x3800
	s_waitcnt lgkmcnt(0)
	s_nop 0
	v_mfma_f32_32x32x16_bf16 v[0:15], v[48:51], v[0:3], 0
	v_mfma_f32_32x32x16_bf16 v[0:15], v[196:199], v[16:19], v[0:15]
	ds_read_b64_tr_b16 v[16:17], v180 offset:0x200
	ds_read_b64_tr_b16 v[18:19], v180 offset:0xa00
	ds_read_b64_tr_b16 v[32:33], v180 offset:0x1200
	ds_read_b64_tr_b16 v[34:35], v180 offset:0x1a00
	ds_read_b64_tr_b16 v[36:37], v180 offset:0x2200
	ds_read_b64_tr_b16 v[38:39], v180 offset:0x2a00
	ds_read_b64_tr_b16 v[40:41], v180 offset:0x3200
	v_mfma_f32_32x32x16_bf16 v[0:15], v[224:227], v[20:23], v[0:15]
	ds_read_b64_tr_b16 v[42:43], v180 offset:0x3a00
	s_waitcnt lgkmcnt(0)
	v_mfma_f32_32x32x16_bf16 v[0:15], v[228:231], v[24:27], v[0:15]
	v_mfma_f32_32x32x16_bf16 v[16:31], v[48:51], v[16:19], 0
	v_mfma_f32_32x32x16_bf16 v[16:31], v[196:199], v[32:35], v[16:31]
	ds_read_b64_tr_b16 v[32:33], v180 offset:0x400
	ds_read_b64_tr_b16 v[34:35], v180 offset:0xc00
	ds_read_b64_tr_b16 v[52:53], v180 offset:0x1400
	ds_read_b64_tr_b16 v[54:55], v180 offset:0x1c00
	ds_read_b64_tr_b16 v[56:57], v180 offset:0x2400
	ds_read_b64_tr_b16 v[58:59], v180 offset:0x2c00
	ds_read_b64_tr_b16 v[60:61], v180 offset:0x3400
	v_mfma_f32_32x32x16_bf16 v[16:31], v[224:227], v[36:39], v[16:31]
	ds_read_b64_tr_b16 v[62:63], v180 offset:0x3c00
	s_waitcnt lgkmcnt(0)
	v_mfma_f32_32x32x16_bf16 v[16:31], v[228:231], v[40:43], v[16:31]
	v_mfma_f32_32x32x16_bf16 v[32:47], v[48:51], v[32:35], 0
	v_mfma_f32_32x32x16_bf16 v[32:47], v[196:199], v[52:55], v[32:47]
	ds_read_b64_tr_b16 v[52:53], v180 offset:0x600
	ds_read_b64_tr_b16 v[54:55], v180 offset:0xe00
	ds_read_b64_tr_b16 v[232:233], v180 offset:0x1600
	ds_read_b64_tr_b16 v[234:235], v180 offset:0x1e00
	ds_read_b64_tr_b16 v[236:237], v180 offset:0x2600
	ds_read_b64_tr_b16 v[238:239], v180 offset:0x2e00
	ds_read_b64_tr_b16 v[240:241], v180 offset:0x3600
	v_mfma_f32_32x32x16_bf16 v[32:47], v[224:227], v[56:59], v[32:47]
	ds_read_b64_tr_b16 v[242:243], v180 offset:0x3e00
	s_waitcnt lgkmcnt(0)
	v_mfma_f32_32x32x16_bf16 v[32:47], v[228:231], v[60:63], v[32:47]
	v_mfma_f32_32x32x16_bf16 v[48:63], v[48:51], v[52:55], 0
	s_barrier
	s_waitcnt vmcnt(0)
	s_mov_b32 s24, 0x43000000
	s_waitcnt vmcnt(5)
	ds_write_b128 v190, v[130:133]
	s_waitcnt vmcnt(4)
	ds_write_b128 v191, v[134:137]
	s_waitcnt vmcnt(3)
	ds_write_b128 v192, v[138:141] offset:32768
	s_waitcnt vmcnt(1)
	ds_write_b128 v193, v[150:153] offset:32768
	ds_write_b128 v203, v[142:145]
	s_waitcnt vmcnt(0)
	ds_write_b128 v204, v[146:149]
	v_mfma_f32_32x32x16_bf16 v[48:63], v[196:199], v[232:235], v[48:63]
	v_max_f32_e32 v196, v81, v81
	v_max_f32_e32 v197, v80, v80
	v_max_f32_e32 v196, v197, v196
	v_max3_f32 v196, v196, v82, v83
	v_max3_f32 v196, v196, v84, v85
	v_max3_f32 v196, v196, v86, v87
	v_max3_f32 v196, v196, v88, v89
	v_max3_f32 v196, v196, v90, v91
	v_max3_f32 v196, v196, v92, v93
	v_max3_f32 v196, v196, v94, v95
	v_max3_f32 v196, v196, v64, v65
	v_max3_f32 v196, v196, v66, v67
	v_max3_f32 v196, v196, v68, v69
	v_max3_f32 v196, v196, v70, v71
	v_max3_f32 v196, v196, v72, v73
	v_mfma_f32_32x32x16_bf16 v[48:63], v[224:227], v[236:239], v[48:63]
	v_max3_f32 v196, v196, v74, v75
	v_max3_f32 v196, v196, v76, v77
	v_max3_f32 v196, v196, v78, v79
	v_mov_b32_e32 v197, v196
	s_nop 1
	v_permlane32_swap_b32_e32 v196, v197
	v_max_f32_e32 v197, v197, v197
	v_max_f32_e32 v196, v196, v196
	v_max_f32_e32 v196, v196, v197
	v_max_f32_e32 v223, v208, v196
	v_mfma_f32_32x32x16_bf16 v[48:63], v[228:231], v[240:243], v[48:63]
	v_sub_f32_e32 v197, v196, v208
	v_sub_f32_e32 v196, v208, v223
	v_mul_f32_e32 v196, 0x3db8aa3b, v196
	v_exp_f32_e32 v196, v196
	v_cmp_ge_f32_e32 vcc, s26, v197
	s_cmp_eq_u64 vcc, exec
	s_cselect_b64 s[36:37], -1, 0
	v_cndmask_b32_e64 v202, v196, 1.0, s[36:37]
	v_cmp_gt_f32_e32 vcc, 1.0, v202
	s_cbranch_vccz .LBB0_469
	s_and_saveexec_b64 s[12:13], s[34:35]
	ds_write_b32 v181, v202 offset:128
	s_or_b64 exec, exec, s[12:13]
	s_waitcnt lgkmcnt(0)
	v_add_u32_e32 v142, v179, v96
	ds_read_b128 v[130:133], v142 offset:224
	ds_read_b128 v[134:137], v142 offset:192
	ds_read_b128 v[138:141], v142 offset:160
	ds_read_b128 v[142:145], v142 offset:128
	s_waitcnt lgkmcnt(3)
	v_pk_mul_f32 v[12:13], v[12:13], v[130:131]
	s_waitcnt lgkmcnt(2)
	v_pk_mul_f32 v[8:9], v[8:9], v[134:135]
	s_waitcnt lgkmcnt(1)
	v_pk_mul_f32 v[4:5], v[4:5], v[138:139]
	v_pk_mul_f32 v[14:15], v[14:15], v[132:133]
	v_pk_mul_f32 v[10:11], v[10:11], v[136:137]
	v_pk_mul_f32 v[6:7], v[6:7], v[140:141]
	s_waitcnt lgkmcnt(0)
	v_pk_mul_f32 v[2:3], v[2:3], v[144:145]
	v_pk_mul_f32 v[0:1], v[0:1], v[142:143]
	v_pk_mul_f32 v[28:29], v[28:29], v[130:131]
	v_pk_mul_f32 v[24:25], v[24:25], v[134:135]
	v_pk_mul_f32 v[20:21], v[20:21], v[138:139]
	v_pk_mul_f32 v[30:31], v[30:31], v[132:133]
	v_pk_mul_f32 v[26:27], v[26:27], v[136:137]
	v_pk_mul_f32 v[22:23], v[22:23], v[140:141]
	v_pk_mul_f32 v[18:19], v[18:19], v[144:145]
	v_pk_mul_f32 v[16:17], v[16:17], v[142:143]
	v_pk_mul_f32 v[44:45], v[44:45], v[130:131]
	v_pk_mul_f32 v[40:41], v[40:41], v[134:135]
	v_pk_mul_f32 v[36:37], v[36:37], v[138:139]
	v_pk_mul_f32 v[46:47], v[46:47], v[132:133]
	v_pk_mul_f32 v[42:43], v[42:43], v[136:137]
	v_pk_mul_f32 v[38:39], v[38:39], v[140:141]
	v_pk_mul_f32 v[34:35], v[34:35], v[144:145]
	v_pk_mul_f32 v[32:33], v[32:33], v[142:143]
	v_pk_mul_f32 v[60:61], v[60:61], v[130:131]
	v_pk_mul_f32 v[56:57], v[56:57], v[134:135]
	v_pk_mul_f32 v[52:53], v[52:53], v[138:139]
	v_pk_mul_f32 v[62:63], v[62:63], v[132:133]
	v_pk_mul_f32 v[58:59], v[58:59], v[136:137]
	v_pk_mul_f32 v[54:55], v[54:55], v[140:141]
	v_pk_mul_f32 v[50:51], v[50:51], v[144:145]
	v_pk_mul_f32 v[48:49], v[48:49], v[142:143]
.LBB0_469:
	v_sub_f32_e32 v130, 0xf149f2ca, v220
	v_mul_f32_e32 v130, 0x3db8aa3b, v130
	v_exp_f32_e32 v204, v130
	s_cmp_lg_u32 0, -1
	v_cndmask_b32_e64 v220, v223, v208, s[36:37]
	s_cselect_b32 s12, 0, 0
	v_mul_f32_e32 v146, 0xbdb8aa3b, v220
	s_addk_i32 s12, 0x4000
	v_and_b32_e32 v203, 0xffffffe0, v154
	v_fmamk_f32 v80, v80, 0x3db8aa3b, v146
	v_fmamk_f32 v81, v81, 0x3db8aa3b, v146
	v_fmamk_f32 v82, v82, 0x3db8aa3b, v146
	v_fmamk_f32 v83, v83, 0x3db8aa3b, v146
	v_fmamk_f32 v84, v84, 0x3db8aa3b, v146
	v_fmamk_f32 v85, v85, 0x3db8aa3b, v146
	v_fmamk_f32 v86, v86, 0x3db8aa3b, v146
	v_fmamk_f32 v87, v87, 0x3db8aa3b, v146
	v_fmamk_f32 v88, v88, 0x3db8aa3b, v146
	v_fmamk_f32 v89, v89, 0x3db8aa3b, v146
	v_fmamk_f32 v90, v90, 0x3db8aa3b, v146
	v_fmamk_f32 v91, v91, 0x3db8aa3b, v146
	v_fmamk_f32 v92, v92, 0x3db8aa3b, v146
	v_fmamk_f32 v93, v93, 0x3db8aa3b, v146
	v_fmamk_f32 v94, v94, 0x3db8aa3b, v146
	v_fmamk_f32 v95, v95, 0x3db8aa3b, v146
	v_fmamk_f32 v154, v75, 0x3db8aa3b, v146
	v_add_u32_e32 v208, s12, v155
	v_fmamk_f32 v223, v64, 0x3db8aa3b, v146
	v_fmamk_f32 v224, v65, 0x3db8aa3b, v146
	v_fmamk_f32 v225, v66, 0x3db8aa3b, v146
	v_fmamk_f32 v226, v67, 0x3db8aa3b, v146
	v_fmamk_f32 v227, v68, 0x3db8aa3b, v146
	v_fmamk_f32 v148, v69, 0x3db8aa3b, v146
	v_fmamk_f32 v149, v70, 0x3db8aa3b, v146
	v_fmamk_f32 v150, v71, 0x3db8aa3b, v146
	v_fmamk_f32 v151, v72, 0x3db8aa3b, v146
	v_fmamk_f32 v152, v73, 0x3db8aa3b, v146
	v_fmamk_f32 v153, v74, 0x3db8aa3b, v146
	v_fmamk_f32 v147, v76, 0x3db8aa3b, v146
	v_exp_f32_e32 v143, v80
	v_exp_f32_e32 v145, v81
	v_exp_f32_e32 v141, v82
	v_exp_f32_e32 v144, v83
	v_exp_f32_e32 v140, v84
	v_exp_f32_e32 v142, v85
	v_exp_f32_e32 v138, v86
	v_exp_f32_e32 v139, v87
	v_exp_f32_e32 v135, v88
	v_exp_f32_e32 v137, v89
	v_exp_f32_e32 v134, v90
	v_exp_f32_e32 v136, v91
	v_exp_f32_e32 v131, v92
	v_exp_f32_e32 v133, v93
	v_exp_f32_e32 v130, v94
	v_exp_f32_e32 v132, v95
	v_fmamk_f32 v228, v77, 0x3db8aa3b, v146
	v_fmamk_f32 v229, v78, 0x3db8aa3b, v146
	v_fmac_f32_e32 v146, 0x3db8aa3b, v79
	s_waitcnt lgkmcnt(0)
	s_barrier
	global_load_dwordx4 v[238:241], v[168:169], off offset:256
	global_load_dwordx4 v[242:245], v[168:169], off offset:288
	global_load_dwordx4 v[246:249], v[168:169], off offset:320
	global_load_dwordx4 v[234:237], v[168:169], off offset:352
	ds_read_b128 v[64:67], v182 offset:32768
	ds_read_b128 v[68:71], v182 offset:40960
	ds_read_b128 v[196:199], v183 offset:32768
	ds_read_b128 v[230:233], v183 offset:40960
	v_exp_f32_e32 v148, v148
	v_exp_f32_e32 v149, v149
	s_waitcnt lgkmcnt(3)
	v_mfma_f32_32x32x16_bf16 v[80:95], v[64:67], v[126:129], 0
	v_exp_f32_e32 v150, v150
	v_exp_f32_e32 v151, v151
	v_exp_f32_e32 v152, v152
	v_exp_f32_e32 v153, v153
	v_exp_f32_e32 v147, v147
	v_exp_f32_e32 v146, v146
	s_waitcnt lgkmcnt(2)
	v_mfma_f32_32x32x16_bf16 v[64:79], v[68:71], v[126:129], 0
	s_waitcnt lgkmcnt(1)
	v_mfma_f32_32x32x16_bf16 v[80:95], v[196:199], v[122:125], v[80:95]
	s_waitcnt lgkmcnt(0)
	v_mfma_f32_32x32x16_bf16 v[64:79], v[230:233], v[122:125], v[64:79]
	ds_read_b128 v[196:199], v184 offset:32768
	ds_read_b128 v[230:233], v184 offset:40960
	s_waitcnt lgkmcnt(1)
	v_mfma_f32_32x32x16_bf16 v[80:95], v[196:199], v[118:121], v[80:95]
	s_waitcnt lgkmcnt(0)
	v_mfma_f32_32x32x16_bf16 v[64:79], v[230:233], v[118:121], v[64:79]
	ds_read_b128 v[196:199], v185 offset:32768
	ds_read_b128 v[230:233], v185 offset:40960
	s_waitcnt lgkmcnt(1)
	v_mfma_f32_32x32x16_bf16 v[80:95], v[196:199], v[114:117], v[80:95]
	s_waitcnt lgkmcnt(0)
	v_mfma_f32_32x32x16_bf16 v[64:79], v[230:233], v[114:117], v[64:79]
	ds_read_b128 v[196:199], v186 offset:32768
	ds_read_b128 v[230:233], v186 offset:40960
	s_waitcnt lgkmcnt(1)
	v_mfma_f32_32x32x16_bf16 v[80:95], v[196:199], v[110:113], v[80:95]
	s_waitcnt lgkmcnt(0)
	v_mfma_f32_32x32x16_bf16 v[64:79], v[230:233], v[110:113], v[64:79]
	ds_read_b128 v[196:199], v187 offset:32768
	ds_read_b128 v[230:233], v187 offset:40960
	s_waitcnt lgkmcnt(1)
	v_mfma_f32_32x32x16_bf16 v[80:95], v[196:199], v[106:109], v[80:95]
	s_waitcnt lgkmcnt(0)
	v_mfma_f32_32x32x16_bf16 v[64:79], v[230:233], v[106:109], v[64:79]
	ds_read_b128 v[196:199], v188 offset:32768
	ds_read_b128 v[230:233], v188 offset:40960
	s_waitcnt lgkmcnt(1)
	v_mfma_f32_32x32x16_bf16 v[80:95], v[196:199], v[102:105], v[80:95]
	s_waitcnt lgkmcnt(0)
	v_mfma_f32_32x32x16_bf16 v[64:79], v[230:233], v[102:105], v[64:79]
	ds_read_b128 v[196:199], v189 offset:32768
	ds_read_b128 v[230:233], v189 offset:40960
	s_waitcnt lgkmcnt(1)
	v_mfma_f32_32x32x16_bf16 v[80:95], v[196:199], v[98:101], v[80:95]
	s_waitcnt lgkmcnt(0)
	v_mfma_f32_32x32x16_bf16 v[64:79], v[230:233], v[98:101], v[64:79]
	ds_read_b128 v[196:199], v156
	ds_read_b128 v[230:233], v156 offset:8192
	s_waitcnt vmcnt(3) lgkmcnt(1)
	v_mfma_f32_32x32x16_bf16 v[80:95], v[196:199], v[238:241], v[80:95]
	s_waitcnt lgkmcnt(0)
	v_mfma_f32_32x32x16_bf16 v[64:79], v[230:233], v[238:241], v[64:79]
	global_load_dwordx4 v[238:241], v[168:169], off offset:384
	ds_read_b128 v[196:199], v157
	ds_read_b128 v[230:233], v157 offset:8192
	s_waitcnt vmcnt(3) lgkmcnt(1)
	v_mfma_f32_32x32x16_bf16 v[80:95], v[196:199], v[242:245], v[80:95]
	s_waitcnt lgkmcnt(0)
	v_mfma_f32_32x32x16_bf16 v[64:79], v[230:233], v[242:245], v[64:79]
	global_load_dwordx4 v[242:245], v[168:169], off offset:416
	ds_read_b128 v[196:199], v205
	ds_read_b128 v[230:233], v205 offset:8192
	s_waitcnt vmcnt(3) lgkmcnt(1)
	v_mfma_f32_32x32x16_bf16 v[80:95], v[196:199], v[246:249], v[80:95]
	s_waitcnt lgkmcnt(0)
	v_mfma_f32_32x32x16_bf16 v[64:79], v[230:233], v[246:249], v[64:79]
	global_load_dwordx4 v[246:249], v[168:169], off offset:448
	ds_read_b128 v[196:199], v207
	ds_read_b128 v[230:233], v207 offset:8192
	v_exp_f32_e32 v207, v223
	v_exp_f32_e32 v223, v227
	s_waitcnt vmcnt(3) lgkmcnt(1)
	v_mfma_f32_32x32x16_bf16 v[80:95], v[196:199], v[234:237], v[80:95]
	s_waitcnt lgkmcnt(0)
	v_mfma_f32_32x32x16_bf16 v[64:79], v[230:233], v[234:237], v[64:79]
	global_load_dwordx4 v[234:237], v[168:169], off offset:480
	ds_read_b128 v[196:199], v209
	ds_read_b128 v[230:233], v209 offset:8192
	v_exp_f32_e32 v209, v224
	s_waitcnt vmcnt(3) lgkmcnt(1)
	v_mfma_f32_32x32x16_bf16 v[80:95], v[196:199], v[238:241], v[80:95]
	s_waitcnt lgkmcnt(0)
	v_mfma_f32_32x32x16_bf16 v[64:79], v[230:233], v[238:241], v[64:79]
	ds_read_b128 v[196:199], v210
	ds_read_b128 v[230:233], v210 offset:8192
	v_exp_f32_e32 v210, v225
	s_waitcnt vmcnt(2) lgkmcnt(1)
	v_mfma_f32_32x32x16_bf16 v[80:95], v[196:199], v[242:245], v[80:95]
	s_waitcnt lgkmcnt(0)
	v_mfma_f32_32x32x16_bf16 v[64:79], v[230:233], v[242:245], v[64:79]
	ds_read_b128 v[196:199], v211
	ds_read_b128 v[230:233], v211 offset:8192
	v_exp_f32_e32 v211, v226
	s_waitcnt vmcnt(1) lgkmcnt(1)
	v_mfma_f32_32x32x16_bf16 v[80:95], v[196:199], v[246:249], v[80:95]
	s_waitcnt lgkmcnt(0)
	v_mfma_f32_32x32x16_bf16 v[64:79], v[230:233], v[246:249], v[64:79]
	ds_read_b128 v[196:199], v206
	ds_read_b128 v[230:233], v206 offset:8192
	s_waitcnt vmcnt(0) lgkmcnt(0)
	v_mfma_f32_32x32x16_bf16 v[64:79], v[230:233], v[234:237], v[64:79]
	v_exp_f32_e32 v230, v154
	v_add_f32_e32 v154, 0, v143
	v_add_f32_e32 v154, v145, v154
	v_add_f32_e32 v154, v141, v154
	v_add_f32_e32 v154, v144, v154
	v_add_f32_e32 v154, v140, v154
	v_add_f32_e32 v154, v142, v154
	v_add_f32_e32 v154, v138, v154
	v_add_f32_e32 v154, v139, v154
	v_add_f32_e32 v154, v135, v154
	v_add_f32_e32 v154, v137, v154
	v_add_f32_e32 v154, v134, v154
	v_add_f32_e32 v154, v136, v154
	v_add_f32_e32 v154, v131, v154
	v_add_f32_e32 v154, v133, v154
	v_add_f32_e32 v154, v130, v154
	v_add_f32_e32 v154, v132, v154
	v_add_f32_e32 v154, v207, v154
	v_add_f32_e32 v154, v209, v154
	v_add_f32_e32 v154, v210, v154
	v_add_f32_e32 v154, v211, v154
	v_add_f32_e32 v154, v223, v154
	v_add_f32_e32 v154, v148, v154
	v_add_f32_e32 v154, v149, v154
	v_add_f32_e32 v154, v150, v154
	v_add_f32_e32 v154, v151, v154
	v_exp_f32_e32 v231, v228
	v_add_f32_e32 v154, v152, v154
	v_mfma_f32_32x32x16_bf16 v[80:95], v[196:199], v[234:237], v[80:95]
	v_exp_f32_e32 v232, v229
	v_add_f32_e32 v154, v153, v154
	v_add_f32_e32 v154, v230, v154
	v_add_f32_e32 v154, v147, v154
	v_add_f32_e32 v154, v231, v154
	v_add_f32_e32 v154, v232, v154
	v_add_f32_e32 v205, v146, v154
	v_mov_b32_e32 v206, v205
	v_cvt_pk_bf16_f32 v154, v143, v145
	v_cvt_pk_bf16_f32 v155, v141, v144
	v_cvt_pk_bf16_f32 v156, v140, v142
	v_cvt_pk_bf16_f32 v157, v138, v139
	s_nop 1
	v_permlane32_swap_b32_e32 v205, v206
	v_permlane32_swap_b32_e32 v154, v156
	v_permlane32_swap_b32_e32 v155, v157
	v_cvt_pk_bf16_f32 v196, v135, v137
	v_cvt_pk_bf16_f32 v197, v134, v136
	v_cvt_pk_bf16_f32 v198, v131, v133
	v_cvt_pk_bf16_f32 v199, v130, v132
	v_cvt_pk_bf16_f32 v224, v207, v209
	v_cvt_pk_bf16_f32 v225, v210, v211
	v_cvt_pk_bf16_f32 v226, v223, v148
	v_cvt_pk_bf16_f32 v227, v149, v150
	v_cvt_pk_bf16_f32 v228, v151, v152
	v_cvt_pk_bf16_f32 v229, v153, v230
	v_cvt_pk_bf16_f32 v230, v147, v231
	v_cvt_pk_bf16_f32 v231, v232, v146
	s_nop 0
	v_permlane32_swap_b32_e32 v196, v198
	v_permlane32_swap_b32_e32 v197, v199
	v_permlane32_swap_b32_e32 v224, v226
	v_permlane32_swap_b32_e32 v225, v227
	v_permlane32_swap_b32_e32 v228, v230
	v_permlane32_swap_b32_e32 v229, v231
	v_lshlrev_b64 v[130:131], 12, v[170:171]
	s_mov_b64 s[12:13], 0xc0000
	v_lshl_add_u64 v[138:139], v[130:131], 0, s[12:13]
	s_mov_b64 s[12:13], 0xe0000
	v_lshl_add_u64 v[140:141], v[130:131], 0, s[12:13]
	v_lshl_add_u64 v[130:131], v[174:175], 0, v[138:139]
	v_lshl_add_u64 v[134:135], v[174:175], 0, v[140:141]
	v_lshl_add_u64 v[142:143], v[172:173], 0, v[138:139]
	v_lshl_add_u64 v[146:147], v[172:173], 0, v[140:141]
	global_load_dwordx4 v[130:133], v[130:131], off offset:2048
	s_nop 0
	global_load_dwordx4 v[134:137], v[134:135], off offset:2048
	s_nop 0
	global_load_dwordx4 v[138:141], v[142:143], off
	s_nop 0
	global_load_dwordx4 v[142:145], v[142:143], off offset:256
	s_nop 0
	global_load_dwordx4 v[150:153], v[146:147], off
	s_nop 0
	global_load_dwordx4 v[146:149], v[146:147], off offset:256
	ds_read_b64_tr_b16 v[170:171], v208 offset:0
	ds_read_b64_tr_b16 v[172:173], v208 offset:0x800
	ds_read_b64_tr_b16 v[232:233], v208 offset:0x1000
	ds_read_b64_tr_b16 v[234:235], v208 offset:0x1800
	ds_read_b64_tr_b16 v[236:237], v208 offset:0x2000
	ds_read_b64_tr_b16 v[238:239], v208 offset:0x2800
	ds_read_b64_tr_b16 v[240:241], v208 offset:0x3000
	ds_read_b64_tr_b16 v[242:243], v208 offset:0x3800
	s_waitcnt lgkmcnt(0)
	s_nop 0
	v_mfma_f32_32x32x16_bf16 v[0:15], v[154:157], v[170:173], v[0:15]
	ds_read_b64_tr_b16 v[170:171], v208 offset:0x200
	ds_read_b64_tr_b16 v[172:173], v208 offset:0xa00
	v_mfma_f32_32x32x16_bf16 v[0:15], v[196:199], v[232:235], v[0:15]
	ds_read_b64_tr_b16 v[232:233], v208 offset:0x1200
	ds_read_b64_tr_b16 v[234:235], v208 offset:0x1a00
	v_mfma_f32_32x32x16_bf16 v[0:15], v[224:227], v[236:239], v[0:15]
	ds_read_b64_tr_b16 v[236:237], v208 offset:0x2200
	ds_read_b64_tr_b16 v[238:239], v208 offset:0x2a00
	v_mfma_f32_32x32x16_bf16 v[0:15], v[228:231], v[240:243], v[0:15]
	ds_read_b64_tr_b16 v[240:241], v208 offset:0x3200
	ds_read_b64_tr_b16 v[242:243], v208 offset:0x3a00
	s_waitcnt lgkmcnt(0)
	v_mfma_f32_32x32x16_bf16 v[16:31], v[154:157], v[170:173], v[16:31]
	ds_read_b64_tr_b16 v[170:171], v208 offset:0x400
	ds_read_b64_tr_b16 v[172:173], v208 offset:0xc00
	v_mfma_f32_32x32x16_bf16 v[16:31], v[196:199], v[232:235], v[16:31]
	ds_read_b64_tr_b16 v[232:233], v208 offset:0x1400
	ds_read_b64_tr_b16 v[234:235], v208 offset:0x1c00
	v_mfma_f32_32x32x16_bf16 v[16:31], v[224:227], v[236:239], v[16:31]
	ds_read_b64_tr_b16 v[236:237], v208 offset:0x2400
	ds_read_b64_tr_b16 v[238:239], v208 offset:0x2c00
	v_mfma_f32_32x32x16_bf16 v[16:31], v[228:231], v[240:243], v[16:31]
	ds_read_b64_tr_b16 v[240:241], v208 offset:0x3400
	ds_read_b64_tr_b16 v[242:243], v208 offset:0x3c00
	s_waitcnt lgkmcnt(0)
	v_mfma_f32_32x32x16_bf16 v[32:47], v[154:157], v[170:173], v[32:47]
	ds_read_b64_tr_b16 v[170:171], v208 offset:0x600
	ds_read_b64_tr_b16 v[172:173], v208 offset:0xe00
	v_mfma_f32_32x32x16_bf16 v[32:47], v[196:199], v[232:235], v[32:47]
	ds_read_b64_tr_b16 v[232:233], v208 offset:0x1600
	ds_read_b64_tr_b16 v[234:235], v208 offset:0x1e00
	v_mfma_f32_32x32x16_bf16 v[32:47], v[224:227], v[236:239], v[32:47]
	ds_read_b64_tr_b16 v[236:237], v208 offset:0x2600
	ds_read_b64_tr_b16 v[238:239], v208 offset:0x2e00
	v_mfma_f32_32x32x16_bf16 v[32:47], v[228:231], v[240:243], v[32:47]
	ds_read_b64_tr_b16 v[240:241], v208 offset:0x3600
	ds_read_b64_tr_b16 v[242:243], v208 offset:0x3e00
	s_waitcnt lgkmcnt(0)
	v_mfma_f32_32x32x16_bf16 v[48:63], v[154:157], v[170:173], v[48:63]
	v_max_f32_e32 v154, v81, v81
	v_max_f32_e32 v155, v80, v80
	v_max_f32_e32 v154, v155, v154
	v_max3_f32 v154, v154, v82, v83
	v_max3_f32 v154, v154, v84, v85
	v_max3_f32 v154, v154, v86, v87
	v_max3_f32 v154, v154, v88, v89
	v_max3_f32 v154, v154, v90, v91
	v_max3_f32 v154, v154, v92, v93
	v_mfma_f32_32x32x16_bf16 v[48:63], v[196:199], v[232:235], v[48:63]
	v_max3_f32 v154, v154, v94, v95
	v_max3_f32 v154, v154, v64, v65
	v_max3_f32 v154, v154, v66, v67
	v_max3_f32 v154, v154, v68, v69
	v_max3_f32 v154, v154, v70, v71
	v_max3_f32 v154, v154, v72, v73
	v_max3_f32 v154, v154, v74, v75
	v_max3_f32 v154, v154, v76, v77
	v_mfma_f32_32x32x16_bf16 v[48:63], v[224:227], v[236:239], v[48:63]
	v_max3_f32 v154, v154, v78, v79
	v_mov_b32_e32 v155, v154
	s_nop 1
	v_permlane32_swap_b32_e32 v154, v155
	v_max_f32_e32 v155, v155, v155
	v_max_f32_e32 v154, v154, v154
	v_max_f32_e32 v154, v154, v155
	v_sub_f32_e32 v155, v154, v220
	v_cmp_ge_f32_e32 vcc, s24, v155
	v_max_f32_e32 v155, v220, v220
	v_max_f32_e32 v155, v155, v154
	v_mfma_f32_32x32x16_bf16 v[48:63], v[228:231], v[240:243], v[48:63]
	v_sub_f32_e32 v154, v220, v155
	v_mul_f32_e32 v154, 0x3db8aa3b, v154
	v_exp_f32_e32 v154, v154
	s_cmp_eq_u64 vcc, exec
	s_cselect_b64 s[36:37], -1, 0
	s_barrier
	s_waitcnt vmcnt(0)
	v_cndmask_b32_e64 v154, v154, 1.0, s[36:37]
	v_cmp_gt_f32_e32 vcc, 1.0, v154
	s_waitcnt vmcnt(5)
	ds_write_b128 v190, v[130:133] offset:16384
	s_waitcnt vmcnt(4)
	ds_write_b128 v191, v[134:137] offset:16384
	s_waitcnt vmcnt(3)
	ds_write_b128 v192, v[138:141] offset:49152
	s_waitcnt vmcnt(1)
	ds_write_b128 v193, v[150:153] offset:49152
	ds_write_b128 v221, v[142:145]
	s_waitcnt vmcnt(0)
	ds_write_b128 v222, v[146:149]
	s_cbranch_vccz .LBB0_473
	s_and_saveexec_b64 s[12:13], s[34:35]
	ds_write_b32 v181, v154 offset:128
	s_or_b64 exec, exec, s[12:13]
	s_waitcnt lgkmcnt(0)
	v_add_u32_e32 v142, v179, v96
	ds_read_b128 v[130:133], v142 offset:224
	ds_read_b128 v[134:137], v142 offset:192
	ds_read_b128 v[138:141], v142 offset:160
	ds_read_b128 v[142:145], v142 offset:128
	s_waitcnt lgkmcnt(3)
	v_pk_mul_f32 v[12:13], v[12:13], v[130:131]
	s_waitcnt lgkmcnt(2)
	v_pk_mul_f32 v[8:9], v[8:9], v[134:135]
	s_waitcnt lgkmcnt(1)
	v_pk_mul_f32 v[4:5], v[4:5], v[138:139]
	v_pk_mul_f32 v[14:15], v[14:15], v[132:133]
	v_pk_mul_f32 v[10:11], v[10:11], v[136:137]
	v_pk_mul_f32 v[6:7], v[6:7], v[140:141]
	s_waitcnt lgkmcnt(0)
	v_pk_mul_f32 v[2:3], v[2:3], v[144:145]
	v_pk_mul_f32 v[0:1], v[0:1], v[142:143]
	v_pk_mul_f32 v[28:29], v[28:29], v[130:131]
	v_pk_mul_f32 v[24:25], v[24:25], v[134:135]
	v_pk_mul_f32 v[20:21], v[20:21], v[138:139]
	v_pk_mul_f32 v[30:31], v[30:31], v[132:133]
	v_pk_mul_f32 v[26:27], v[26:27], v[136:137]
	v_pk_mul_f32 v[22:23], v[22:23], v[140:141]
	v_pk_mul_f32 v[18:19], v[18:19], v[144:145]
	v_pk_mul_f32 v[16:17], v[16:17], v[142:143]
	v_pk_mul_f32 v[44:45], v[44:45], v[130:131]
	v_pk_mul_f32 v[40:41], v[40:41], v[134:135]
	v_pk_mul_f32 v[36:37], v[36:37], v[138:139]
	v_pk_mul_f32 v[46:47], v[46:47], v[132:133]
	v_pk_mul_f32 v[42:43], v[42:43], v[136:137]
	v_pk_mul_f32 v[38:39], v[38:39], v[140:141]
	v_pk_mul_f32 v[34:35], v[34:35], v[144:145]
	v_pk_mul_f32 v[32:33], v[32:33], v[142:143]
	v_pk_mul_f32 v[60:61], v[60:61], v[130:131]
	v_pk_mul_f32 v[56:57], v[56:57], v[134:135]
	v_pk_mul_f32 v[52:53], v[52:53], v[138:139]
	v_pk_mul_f32 v[62:63], v[62:63], v[132:133]
	v_pk_mul_f32 v[58:59], v[58:59], v[136:137]
	v_pk_mul_f32 v[54:55], v[54:55], v[140:141]
	v_pk_mul_f32 v[50:51], v[50:51], v[144:145]
	v_pk_mul_f32 v[48:49], v[48:49], v[142:143]
.LBB0_473:
	v_cndmask_b32_e64 v130, v155, v220, s[36:37]
	v_mul_f32_e32 v147, 0xbdb8aa3b, v130
	v_fmamk_f32 v80, v80, 0x3db8aa3b, v147
	v_fmamk_f32 v81, v81, 0x3db8aa3b, v147
	v_fmamk_f32 v82, v82, 0x3db8aa3b, v147
	v_fmamk_f32 v83, v83, 0x3db8aa3b, v147
	v_fmamk_f32 v84, v84, 0x3db8aa3b, v147
	v_fmamk_f32 v85, v85, 0x3db8aa3b, v147
	v_fmamk_f32 v86, v86, 0x3db8aa3b, v147
	v_fmamk_f32 v87, v87, 0x3db8aa3b, v147
	v_fmamk_f32 v88, v88, 0x3db8aa3b, v147
	v_fmamk_f32 v89, v89, 0x3db8aa3b, v147
	v_fmamk_f32 v90, v90, 0x3db8aa3b, v147
	v_fmamk_f32 v91, v91, 0x3db8aa3b, v147
	v_fmamk_f32 v92, v92, 0x3db8aa3b, v147
	v_fmamk_f32 v93, v93, 0x3db8aa3b, v147
	v_fmamk_f32 v94, v94, 0x3db8aa3b, v147
	v_fmamk_f32 v95, v95, 0x3db8aa3b, v147
	v_fmamk_f32 v157, v64, 0x3db8aa3b, v147
	v_fmamk_f32 v170, v65, 0x3db8aa3b, v147
	v_fmamk_f32 v171, v66, 0x3db8aa3b, v147
	v_fmamk_f32 v172, v67, 0x3db8aa3b, v147
	v_fmamk_f32 v173, v68, 0x3db8aa3b, v147
	v_fmamk_f32 v149, v69, 0x3db8aa3b, v147
	v_fmamk_f32 v150, v70, 0x3db8aa3b, v147
	v_fmamk_f32 v151, v71, 0x3db8aa3b, v147
	v_fmamk_f32 v152, v72, 0x3db8aa3b, v147
	v_fmamk_f32 v153, v73, 0x3db8aa3b, v147
	v_fmamk_f32 v155, v74, 0x3db8aa3b, v147
	v_fmamk_f32 v156, v75, 0x3db8aa3b, v147
	v_fmamk_f32 v148, v76, 0x3db8aa3b, v147
	v_exp_f32_e32 v144, v80
	v_exp_f32_e32 v146, v81
	v_exp_f32_e32 v142, v82
	v_exp_f32_e32 v145, v83
	v_exp_f32_e32 v141, v84
	v_exp_f32_e32 v143, v85
	v_exp_f32_e32 v139, v86
	v_exp_f32_e32 v140, v87
	v_exp_f32_e32 v136, v88
	v_exp_f32_e32 v138, v89
	v_exp_f32_e32 v135, v90
	v_exp_f32_e32 v137, v91
	v_exp_f32_e32 v132, v92
	v_exp_f32_e32 v134, v93
	v_exp_f32_e32 v131, v94
	v_exp_f32_e32 v133, v95
	v_fmamk_f32 v174, v77, 0x3db8aa3b, v147
	v_fmamk_f32 v175, v78, 0x3db8aa3b, v147
	v_fmac_f32_e32 v147, 0x3db8aa3b, v79
	s_waitcnt lgkmcnt(0)
	s_barrier
	global_load_dwordx4 v[220:223], v[168:169], off offset:256
	global_load_dwordx4 v[224:227], v[168:169], off offset:288
	global_load_dwordx4 v[228:231], v[168:169], off offset:320
	global_load_dwordx4 v[232:235], v[168:169], off offset:352
	global_load_dwordx4 v[236:239], v[168:169], off offset:384
	global_load_dwordx4 v[240:243], v[168:169], off offset:416
	global_load_dwordx4 v[244:247], v[168:169], off offset:448
	global_load_dwordx4 v[196:199], v[168:169], off offset:480
	ds_read_b128 v[64:67], v182 offset:49152
	ds_read_b128 v[68:71], v182 offset:57344
	s_waitcnt lgkmcnt(1)
	v_mfma_f32_32x32x16_bf16 v[80:95], v[64:67], v[126:129], 0
	s_waitcnt lgkmcnt(0)
	v_mfma_f32_32x32x16_bf16 v[64:79], v[68:71], v[126:129], 0
	ds_read_b128 v[126:129], v183 offset:49152
	ds_read_b128 v[190:193], v183 offset:57344
	s_waitcnt lgkmcnt(1)
	v_mfma_f32_32x32x16_bf16 v[80:95], v[126:129], v[122:125], v[80:95]
	s_waitcnt lgkmcnt(0)
	v_mfma_f32_32x32x16_bf16 v[64:79], v[190:193], v[122:125], v[64:79]
	ds_read_b128 v[122:125], v184 offset:49152
	ds_read_b128 v[126:129], v184 offset:57344
	s_waitcnt lgkmcnt(1)
	v_mfma_f32_32x32x16_bf16 v[80:95], v[122:125], v[118:121], v[80:95]
	s_waitcnt lgkmcnt(0)
	v_mfma_f32_32x32x16_bf16 v[64:79], v[126:129], v[118:121], v[64:79]
	ds_read_b128 v[118:121], v185 offset:49152
	ds_read_b128 v[122:125], v185 offset:57344
	s_waitcnt lgkmcnt(1)
	v_mfma_f32_32x32x16_bf16 v[80:95], v[118:121], v[114:117], v[80:95]
	s_waitcnt lgkmcnt(0)
	v_mfma_f32_32x32x16_bf16 v[64:79], v[122:125], v[114:117], v[64:79]
	ds_read_b128 v[114:117], v186 offset:49152
	ds_read_b128 v[118:121], v186 offset:57344
	v_exp_f32_e32 v122, v175
	v_exp_f32_e32 v123, v147
	s_waitcnt lgkmcnt(1)
	v_mfma_f32_32x32x16_bf16 v[80:95], v[114:117], v[110:113], v[80:95]
	s_waitcnt lgkmcnt(0)
	v_mfma_f32_32x32x16_bf16 v[64:79], v[118:121], v[110:113], v[64:79]
	ds_read_b128 v[110:113], v187 offset:49152
	ds_read_b128 v[114:117], v187 offset:57344
	v_exp_f32_e32 v118, v155
	v_exp_f32_e32 v119, v156
	v_exp_f32_e32 v120, v148
	v_exp_f32_e32 v121, v174
	s_waitcnt lgkmcnt(1)
	v_mfma_f32_32x32x16_bf16 v[80:95], v[110:113], v[106:109], v[80:95]
	s_waitcnt lgkmcnt(0)
	v_mfma_f32_32x32x16_bf16 v[64:79], v[114:117], v[106:109], v[64:79]
	ds_read_b128 v[106:109], v188 offset:49152
	ds_read_b128 v[110:113], v188 offset:57344
	v_exp_f32_e32 v114, v150
	v_exp_f32_e32 v115, v151
	v_exp_f32_e32 v116, v152
	v_exp_f32_e32 v117, v153
	s_waitcnt lgkmcnt(1)
	v_mfma_f32_32x32x16_bf16 v[80:95], v[106:109], v[102:105], v[80:95]
	s_waitcnt lgkmcnt(0)
	v_mfma_f32_32x32x16_bf16 v[64:79], v[110:113], v[102:105], v[64:79]
	ds_read_b128 v[102:105], v189 offset:49152
	ds_read_b128 v[106:109], v189 offset:57344
	v_exp_f32_e32 v110, v171
	v_exp_f32_e32 v111, v172
	v_exp_f32_e32 v112, v173
	v_exp_f32_e32 v113, v149
	s_waitcnt lgkmcnt(1)
	v_mfma_f32_32x32x16_bf16 v[80:95], v[102:105], v[98:101], v[80:95]
	s_waitcnt lgkmcnt(0)
	v_mfma_f32_32x32x16_bf16 v[64:79], v[106:109], v[98:101], v[64:79]
	ds_read_b128 v[98:101], v212
	ds_read_b128 v[102:105], v212 offset:8192
	s_waitcnt vmcnt(7) lgkmcnt(1)
	v_mfma_f32_32x32x16_bf16 v[80:95], v[98:101], v[220:223], v[80:95]
	s_waitcnt lgkmcnt(0)
	v_mfma_f32_32x32x16_bf16 v[64:79], v[102:105], v[220:223], v[64:79]
	ds_read_b128 v[98:101], v213
	ds_read_b128 v[102:105], v213 offset:8192
	s_waitcnt vmcnt(6) lgkmcnt(1)
	v_mfma_f32_32x32x16_bf16 v[80:95], v[98:101], v[224:227], v[80:95]
	s_waitcnt lgkmcnt(0)
	v_mfma_f32_32x32x16_bf16 v[64:79], v[102:105], v[224:227], v[64:79]
	ds_read_b128 v[98:101], v215
	ds_read_b128 v[102:105], v215 offset:8192
	s_waitcnt vmcnt(5) lgkmcnt(1)
	v_mfma_f32_32x32x16_bf16 v[80:95], v[98:101], v[228:231], v[80:95]
	s_waitcnt lgkmcnt(0)
	v_mfma_f32_32x32x16_bf16 v[64:79], v[102:105], v[228:231], v[64:79]
	ds_read_b128 v[98:101], v214
	ds_read_b128 v[102:105], v214 offset:8192
	s_waitcnt vmcnt(4) lgkmcnt(1)
	v_mfma_f32_32x32x16_bf16 v[80:95], v[98:101], v[232:235], v[80:95]
	s_waitcnt lgkmcnt(0)
	v_mfma_f32_32x32x16_bf16 v[64:79], v[102:105], v[232:235], v[64:79]
	ds_read_b128 v[98:101], v217
	ds_read_b128 v[102:105], v217 offset:8192
	s_waitcnt vmcnt(3) lgkmcnt(1)
	v_mfma_f32_32x32x16_bf16 v[80:95], v[98:101], v[236:239], v[80:95]
	s_waitcnt lgkmcnt(0)
	v_mfma_f32_32x32x16_bf16 v[64:79], v[102:105], v[236:239], v[64:79]
	ds_read_b128 v[98:101], v216
	ds_read_b128 v[102:105], v216 offset:8192
	s_waitcnt vmcnt(2) lgkmcnt(1)
	v_mfma_f32_32x32x16_bf16 v[80:95], v[98:101], v[240:243], v[80:95]
	s_waitcnt lgkmcnt(0)
	v_mfma_f32_32x32x16_bf16 v[64:79], v[102:105], v[240:243], v[64:79]
	ds_read_b128 v[98:101], v218
	ds_read_b128 v[102:105], v218 offset:8192
	s_waitcnt vmcnt(1) lgkmcnt(1)
	v_mfma_f32_32x32x16_bf16 v[80:95], v[98:101], v[244:247], v[80:95]
	s_waitcnt lgkmcnt(0)
	v_mfma_f32_32x32x16_bf16 v[64:79], v[102:105], v[244:247], v[64:79]
	ds_read_b128 v[98:101], v219
	ds_read_b128 v[102:105], v219 offset:8192
	s_waitcnt vmcnt(0) lgkmcnt(1)
	v_mfma_f32_32x32x16_bf16 v[80:95], v[98:101], v[196:199], v[80:95]
	v_add_f32_e32 v98, 0, v144
	v_add_f32_e32 v98, v146, v98
	v_add_f32_e32 v98, v142, v98
	v_add_f32_e32 v98, v145, v98
	v_add_f32_e32 v98, v141, v98
	v_add_f32_e32 v98, v143, v98
	v_add_f32_e32 v98, v139, v98
	v_add_f32_e32 v98, v140, v98
	v_add_f32_e32 v98, v136, v98
	v_add_f32_e32 v98, v138, v98
	v_add_f32_e32 v98, v135, v98
	v_add_f32_e32 v98, v137, v98
	s_waitcnt lgkmcnt(0)
	v_mfma_f32_32x32x16_bf16 v[64:79], v[102:105], v[196:199], v[64:79]
	v_exp_f32_e32 v108, v157
	v_add_f32_e32 v98, v132, v98
	v_exp_f32_e32 v109, v170
	v_add_f32_e32 v98, v134, v98
	v_add_f32_e32 v98, v131, v98
	v_add_f32_e32 v98, v133, v98
	v_add_f32_e32 v98, v108, v98
	v_add_f32_e32 v98, v109, v98
	v_add_f32_e32 v98, v110, v98
	v_add_f32_e32 v98, v111, v98
	v_add_f32_e32 v98, v112, v98
	v_add_f32_e32 v98, v113, v98
	v_add_f32_e32 v98, v114, v98
	v_add_f32_e32 v98, v115, v98
	v_add_f32_e32 v98, v116, v98
	v_add_f32_e32 v98, v117, v98
	v_add_f32_e32 v98, v118, v98
	v_add_f32_e32 v98, v119, v98
	v_add_f32_e32 v98, v120, v98
	v_add_f32_e32 v98, v121, v98
	v_add_f32_e32 v98, v122, v98
	v_add_f32_e32 v106, v123, v98
	v_mov_b32_e32 v107, v106
	v_cvt_pk_bf16_f32 v98, v144, v146
	v_cvt_pk_bf16_f32 v99, v142, v145
	v_cvt_pk_bf16_f32 v100, v141, v143
	v_cvt_pk_bf16_f32 v101, v139, v140
	s_nop 1
	v_permlane32_swap_b32_e32 v106, v107
	v_permlane32_swap_b32_e32 v98, v100
	v_permlane32_swap_b32_e32 v99, v101
	v_cvt_pk_bf16_f32 v102, v136, v138
	v_cvt_pk_bf16_f32 v103, v135, v137
	v_cvt_pk_bf16_f32 v104, v132, v134
	v_cvt_pk_bf16_f32 v105, v131, v133
	v_cvt_pk_bf16_f32 v108, v108, v109
	v_cvt_pk_bf16_f32 v109, v110, v111
	v_cvt_pk_bf16_f32 v110, v112, v113
	v_cvt_pk_bf16_f32 v111, v114, v115
	v_cvt_pk_bf16_f32 v112, v116, v117
	v_cvt_pk_bf16_f32 v113, v118, v119
	v_cvt_pk_bf16_f32 v114, v120, v121
	v_cvt_pk_bf16_f32 v115, v122, v123
	s_nop 0
	v_permlane32_swap_b32_e32 v102, v104
	v_permlane32_swap_b32_e32 v103, v105
	v_permlane32_swap_b32_e32 v108, v110
	v_permlane32_swap_b32_e32 v109, v111
	v_permlane32_swap_b32_e32 v112, v114
	v_permlane32_swap_b32_e32 v113, v115
	ds_read_b64_tr_b16 v[116:117], v180 offset:0
	ds_read_b64_tr_b16 v[118:119], v180 offset:0x800
	ds_read_b64_tr_b16 v[120:121], v180 offset:0x1000
	ds_read_b64_tr_b16 v[122:123], v180 offset:0x1800
	ds_read_b64_tr_b16 v[124:125], v180 offset:0x2000
	ds_read_b64_tr_b16 v[126:127], v180 offset:0x2800
	ds_read_b64_tr_b16 v[132:133], v180 offset:0x3000
	ds_read_b64_tr_b16 v[134:135], v180 offset:0x3800
	s_waitcnt lgkmcnt(0)
	s_nop 0
	v_mfma_f32_32x32x16_bf16 v[0:15], v[98:101], v[116:119], v[0:15]
	ds_read_b64_tr_b16 v[116:117], v180 offset:0x200
	ds_read_b64_tr_b16 v[118:119], v180 offset:0xa00
	v_mfma_f32_32x32x16_bf16 v[0:15], v[102:105], v[120:123], v[0:15]
	ds_read_b64_tr_b16 v[120:121], v180 offset:0x1200
	ds_read_b64_tr_b16 v[122:123], v180 offset:0x1a00
	v_mfma_f32_32x32x16_bf16 v[0:15], v[108:111], v[124:127], v[0:15]
	ds_read_b64_tr_b16 v[124:125], v180 offset:0x2200
	ds_read_b64_tr_b16 v[126:127], v180 offset:0x2a00
	v_mfma_f32_32x32x16_bf16 v[0:15], v[112:115], v[132:135], v[0:15]
	ds_read_b64_tr_b16 v[132:133], v180 offset:0x3200
	ds_read_b64_tr_b16 v[134:135], v180 offset:0x3a00
	s_waitcnt lgkmcnt(0)
	v_mfma_f32_32x32x16_bf16 v[16:31], v[98:101], v[116:119], v[16:31]
	ds_read_b64_tr_b16 v[116:117], v180 offset:0x400
	ds_read_b64_tr_b16 v[118:119], v180 offset:0xc00
	v_mfma_f32_32x32x16_bf16 v[16:31], v[102:105], v[120:123], v[16:31]
	ds_read_b64_tr_b16 v[120:121], v180 offset:0x1400
	ds_read_b64_tr_b16 v[122:123], v180 offset:0x1c00
	v_mfma_f32_32x32x16_bf16 v[16:31], v[108:111], v[124:127], v[16:31]
	ds_read_b64_tr_b16 v[124:125], v180 offset:0x2400
	ds_read_b64_tr_b16 v[126:127], v180 offset:0x2c00
	v_mfma_f32_32x32x16_bf16 v[16:31], v[112:115], v[132:135], v[16:31]
	ds_read_b64_tr_b16 v[132:133], v180 offset:0x3400
	ds_read_b64_tr_b16 v[134:135], v180 offset:0x3c00
	s_waitcnt lgkmcnt(0)
	v_mfma_f32_32x32x16_bf16 v[32:47], v[98:101], v[116:119], v[32:47]
	ds_read_b64_tr_b16 v[116:117], v180 offset:0x600
	ds_read_b64_tr_b16 v[118:119], v180 offset:0xe00
	v_mfma_f32_32x32x16_bf16 v[32:47], v[102:105], v[120:123], v[32:47]
	ds_read_b64_tr_b16 v[120:121], v180 offset:0x1600
	ds_read_b64_tr_b16 v[122:123], v180 offset:0x1e00
	v_mfma_f32_32x32x16_bf16 v[32:47], v[108:111], v[124:127], v[32:47]
	ds_read_b64_tr_b16 v[124:125], v180 offset:0x2600
	ds_read_b64_tr_b16 v[126:127], v180 offset:0x2e00
	v_mfma_f32_32x32x16_bf16 v[32:47], v[112:115], v[132:135], v[32:47]
	ds_read_b64_tr_b16 v[132:133], v180 offset:0x3600
	ds_read_b64_tr_b16 v[134:135], v180 offset:0x3e00
	s_waitcnt lgkmcnt(0)
	v_mfma_f32_32x32x16_bf16 v[48:63], v[98:101], v[116:119], v[48:63]
	v_max_f32_e32 v98, v81, v81
	v_max_f32_e32 v99, v80, v80
	v_max_f32_e32 v98, v99, v98
	v_max3_f32 v98, v98, v82, v83
	v_max3_f32 v98, v98, v84, v85
	v_max3_f32 v98, v98, v86, v87
	v_max3_f32 v98, v98, v88, v89
	v_max3_f32 v98, v98, v90, v91
	v_max3_f32 v98, v98, v92, v93
	v_mfma_f32_32x32x16_bf16 v[48:63], v[102:105], v[120:123], v[48:63]
	v_max3_f32 v98, v98, v94, v95
	v_max3_f32 v98, v98, v64, v65
	v_max3_f32 v98, v98, v66, v67
	v_max3_f32 v98, v98, v68, v69
	v_max3_f32 v98, v98, v70, v71
	v_max3_f32 v98, v98, v72, v73
	v_max3_f32 v98, v98, v74, v75
	v_max3_f32 v98, v98, v76, v77
	v_mfma_f32_32x32x16_bf16 v[48:63], v[108:111], v[124:127], v[48:63]
	v_max3_f32 v98, v98, v78, v79
	v_mov_b32_e32 v99, v98
	s_nop 1
	v_permlane32_swap_b32_e32 v98, v99
	v_max_f32_e32 v99, v99, v99
	v_max_f32_e32 v98, v98, v98
	v_max_f32_e32 v98, v98, v99
	v_sub_f32_e32 v99, v98, v130
	v_cmp_ge_f32_e32 vcc, s24, v99
	v_max_f32_e32 v99, v130, v130
	v_max_f32_e32 v99, v99, v98
	v_mfma_f32_32x32x16_bf16 v[48:63], v[112:115], v[132:135], v[48:63]
	v_sub_f32_e32 v98, v130, v99
	v_mul_f32_e32 v98, 0x3db8aa3b, v98
	v_exp_f32_e32 v98, v98
	s_cmp_eq_u64 vcc, exec
	s_cselect_b64 s[36:37], -1, 0
	v_cndmask_b32_e64 v98, v98, 1.0, s[36:37]
	v_cmp_gt_f32_e32 vcc, 1.0, v98
	s_barrier
	s_cbranch_vccz .LBB0_477
	s_and_saveexec_b64 s[12:13], s[34:35]
	ds_write_b32 v181, v98 offset:128
	s_or_b64 exec, exec, s[12:13]
	s_waitcnt lgkmcnt(0)
	v_add_u32_e32 v104, v179, v96
	ds_read_b128 v[100:103], v104 offset:224
	ds_read_b128 v[108:111], v104 offset:192
	ds_read_b128 v[112:115], v104 offset:160
	ds_read_b128 v[116:119], v104 offset:128
	s_waitcnt lgkmcnt(3)
	v_pk_mul_f32 v[12:13], v[12:13], v[100:101]
	s_waitcnt lgkmcnt(2)
	v_pk_mul_f32 v[8:9], v[8:9], v[108:109]
	s_waitcnt lgkmcnt(1)
	v_pk_mul_f32 v[4:5], v[4:5], v[112:113]
	v_pk_mul_f32 v[14:15], v[14:15], v[102:103]
	v_pk_mul_f32 v[10:11], v[10:11], v[110:111]
	v_pk_mul_f32 v[6:7], v[6:7], v[114:115]
	s_waitcnt lgkmcnt(0)
	v_pk_mul_f32 v[2:3], v[2:3], v[118:119]
	v_pk_mul_f32 v[0:1], v[0:1], v[116:117]
	v_pk_mul_f32 v[28:29], v[28:29], v[100:101]
	v_pk_mul_f32 v[24:25], v[24:25], v[108:109]
	v_pk_mul_f32 v[20:21], v[20:21], v[112:113]
	v_pk_mul_f32 v[30:31], v[30:31], v[102:103]
	v_pk_mul_f32 v[26:27], v[26:27], v[110:111]
	v_pk_mul_f32 v[22:23], v[22:23], v[114:115]
	v_pk_mul_f32 v[18:19], v[18:19], v[118:119]
	v_pk_mul_f32 v[16:17], v[16:17], v[116:117]
	v_pk_mul_f32 v[44:45], v[44:45], v[100:101]
	v_pk_mul_f32 v[40:41], v[40:41], v[108:109]
	v_pk_mul_f32 v[36:37], v[36:37], v[112:113]
	v_pk_mul_f32 v[46:47], v[46:47], v[102:103]
	v_pk_mul_f32 v[42:43], v[42:43], v[110:111]
	v_pk_mul_f32 v[38:39], v[38:39], v[114:115]
	v_pk_mul_f32 v[34:35], v[34:35], v[118:119]
	v_pk_mul_f32 v[32:33], v[32:33], v[116:117]
	v_pk_mul_f32 v[60:61], v[60:61], v[100:101]
	v_pk_mul_f32 v[56:57], v[56:57], v[108:109]
	v_pk_mul_f32 v[52:53], v[52:53], v[112:113]
	v_pk_mul_f32 v[62:63], v[62:63], v[102:103]
	v_pk_mul_f32 v[58:59], v[58:59], v[110:111]
	v_pk_mul_f32 v[54:55], v[54:55], v[114:115]
	v_pk_mul_f32 v[50:51], v[50:51], v[118:119]
	v_pk_mul_f32 v[48:49], v[48:49], v[116:117]
